# E4g + MLA: s_setprio 1 raised before the first K-fragment LDS reads of each QK segment
# baseline (speedup 1.0000x reference)
.Lmla_dma1_ret:
	s_setprio 1
	ds_read_b128 v[80:83], v227 offset:32768
	ds_read_b128 v[84:87], v227 offset:40960
	ds_read_b128 v[88:91], v228 offset:32768
	ds_read_b128 v[92:95], v228 offset:40960
	s_add_i32 s16, s82, 0xffffff80
	s_add_i32 s14, s82, 0xffffffbf
	ds_read_b128 v[232:235], v229 offset:32768
	ds_read_b128 v[236:239], v229 offset:40960
	s_waitcnt lgkmcnt(5)
	v_mfma_f32_32x32x16_bf16 v[112:127], v[80:83], v[130:133], v[64:79]
	s_waitcnt lgkmcnt(4)
	v_mfma_f32_32x32x16_bf16 v[96:111], v[84:87], v[130:133], v[64:79]
	ds_read_b128 v[80:83], v230 offset:32768
	ds_read_b128 v[84:87], v230 offset:40960
	s_waitcnt lgkmcnt(5)
	v_mfma_f32_32x32x16_bf16 v[112:127], v[88:91], v[134:137], v[112:127]
	s_waitcnt lgkmcnt(4)
	v_mfma_f32_32x32x16_bf16 v[96:111], v[92:95], v[134:137], v[96:111]
	ds_read_b128 v[88:91], v227 offset:32896
	ds_read_b128 v[92:95], v227 offset:41088
	s_waitcnt lgkmcnt(5)
	v_mfma_f32_32x32x16_bf16 v[112:127], v[232:235], v[138:141], v[112:127]
	s_waitcnt lgkmcnt(4)
	v_mfma_f32_32x32x16_bf16 v[96:111], v[236:239], v[138:141], v[96:111]
	ds_read_b128 v[232:235], v228 offset:32896
	ds_read_b128 v[236:239], v228 offset:41088
	s_waitcnt lgkmcnt(5)
	v_mfma_f32_32x32x16_bf16 v[112:127], v[80:83], v[142:145], v[112:127]
	s_waitcnt lgkmcnt(4)
	v_mfma_f32_32x32x16_bf16 v[96:111], v[84:87], v[142:145], v[96:111]
	ds_read_b128 v[80:83], v229 offset:32896
	ds_read_b128 v[84:87], v229 offset:41088
	s_waitcnt lgkmcnt(5)
	v_mfma_f32_32x32x16_bf16 v[112:127], v[88:91], v[162:165], v[112:127]
	s_waitcnt lgkmcnt(4)
	v_mfma_f32_32x32x16_bf16 v[96:111], v[92:95], v[162:165], v[96:111]
	ds_read_b128 v[88:91], v230 offset:32896
	ds_read_b128 v[92:95], v230 offset:41088
	s_waitcnt lgkmcnt(5)
	v_mfma_f32_32x32x16_bf16 v[112:127], v[232:235], v[166:169], v[112:127]
	s_waitcnt lgkmcnt(4)
	v_mfma_f32_32x32x16_bf16 v[96:111], v[236:239], v[166:169], v[96:111]
	v_add_u32_e32 v178, v187, v220
	ds_read_b128 v[232:235], v178 offset:4096
	ds_read_b128 v[236:239], v178
	ds_read_b128 v[240:243], v213
	s_waitcnt lgkmcnt(6)
	v_mfma_f32_32x32x16_bf16 v[112:127], v[80:83], v[170:173], v[112:127]
	s_waitcnt lgkmcnt(5)
	v_mfma_f32_32x32x16_bf16 v[96:111], v[84:87], v[170:173], v[96:111]
	v_add_u32_e32 v84, v187, v221
	ds_read_b128 v[80:83], v84 offset:4096
	ds_read_b128 v[84:87], v84
	ds_read_b128 v[244:247], v213 offset:1024
	s_waitcnt lgkmcnt(7)
	v_mfma_f32_32x32x16_bf16 v[112:127], v[88:91], v[174:177], v[112:127]
	s_waitcnt lgkmcnt(6)
	v_mfma_f32_32x32x16_bf16 v[96:111], v[92:95], v[174:177], v[96:111]
	v_add_u32_e32 v92, v187, v222
	ds_read_b128 v[88:91], v92 offset:4096
	ds_read_b128 v[92:95], v92
	ds_read_b128 v[248:251], v213 offset:2048
	s_waitcnt lgkmcnt(6)
	v_mfma_f32_32x32x16_bf16 v[112:127], v[236:239], v[240:243], v[112:127]
	v_mfma_f32_32x32x16_bf16 v[96:111], v[232:235], v[240:243], v[96:111]
	v_add_u32_e32 v178, v187, v223
	ds_read_b128 v[232:235], v178 offset:4096
	ds_read_b128 v[236:239], v178
	ds_read_b128 v[240:243], v213 offset:3072
	s_waitcnt lgkmcnt(6)
	v_mfma_f32_32x32x16_bf16 v[112:127], v[84:87], v[244:247], v[112:127]
	v_mfma_f32_32x32x16_bf16 v[96:111], v[80:83], v[244:247], v[96:111]
	s_waitcnt lgkmcnt(3)
	v_mfma_f32_32x32x16_bf16 v[112:127], v[92:95], v[248:251], v[112:127]
	v_mfma_f32_32x32x16_bf16 v[96:111], v[88:91], v[248:251], v[96:111]
	s_waitcnt lgkmcnt(0)
	v_mfma_f32_32x32x16_bf16 v[112:127], v[236:239], v[240:243], v[112:127]
	v_mfma_f32_32x32x16_bf16 v[96:111], v[232:235], v[240:243], v[96:111]
	s_setprio 0
	s_cmp_le_i32 s14, s12
	s_cselect_b64 s[14:15], -1, 0
	s_cmp_gt_i32 s16, s22
	s_cselect_b64 s[44:45], -1, 0
	s_and_b64 s[14:15], s[14:15], s[44:45]
	s_and_b64 vcc, exec, s[14:15]
	s_cbranch_vccnz .LBB0_830
	v_add_u32_e32 v80, 59, v225
	v_cmp_gt_u32_e32 vcc, s35, v80
	v_add_u32_e32 v80, 27, v225
	s_nop 0
	v_cndmask_b32_e32 v112, v202, v112, vcc
	v_cmp_gt_u32_e32 vcc, s35, v80
	v_add_u32_e32 v80, 58, v225
	s_nop 0
	v_cndmask_b32_e32 v96, v202, v96, vcc
	v_cmp_gt_u32_e32 vcc, s35, v80
	v_add_u32_e32 v80, 26, v225
	s_nop 0
	v_cndmask_b32_e32 v113, v202, v113, vcc
	v_cmp_gt_u32_e32 vcc, s35, v80
	v_add_u32_e32 v80, 57, v225
	s_nop 0
	v_cndmask_b32_e32 v97, v202, v97, vcc
	v_cmp_gt_u32_e32 vcc, s35, v80
	v_add_u32_e32 v80, 25, v225
	s_nop 0
	v_cndmask_b32_e32 v114, v202, v114, vcc
	v_cmp_gt_u32_e32 vcc, s35, v80
	v_add_u32_e32 v80, 56, v225
	s_nop 0
	v_cndmask_b32_e32 v98, v202, v98, vcc
	v_cmp_gt_u32_e32 vcc, s35, v80
	v_add_u32_e32 v80, 24, v225
	s_nop 0
	v_cndmask_b32_e32 v115, v202, v115, vcc
	v_cmp_gt_u32_e32 vcc, s35, v80
	v_add_u32_e32 v80, 51, v225
	s_nop 0
	v_cndmask_b32_e32 v99, v202, v99, vcc
	v_cmp_gt_u32_e32 vcc, s35, v80
	v_add_u32_e32 v80, 19, v225
	s_nop 0
	v_cndmask_b32_e32 v116, v202, v116, vcc
	v_cmp_gt_u32_e32 vcc, s35, v80
	v_add_u32_e32 v80, 50, v225
	s_nop 0
	v_cndmask_b32_e32 v100, v202, v100, vcc
	v_cmp_gt_u32_e32 vcc, s35, v80
	v_add_u32_e32 v80, 18, v225
	s_nop 0
	v_cndmask_b32_e32 v117, v202, v117, vcc
	v_cmp_gt_u32_e32 vcc, s35, v80
	v_add_u32_e32 v80, 49, v225
	s_nop 0
	v_cndmask_b32_e32 v101, v202, v101, vcc
	v_cmp_gt_u32_e32 vcc, s35, v80
	v_add_u32_e32 v80, 17, v225
	s_nop 0
	v_cndmask_b32_e32 v118, v202, v118, vcc
	v_cmp_gt_u32_e32 vcc, s35, v80
	v_add_u32_e32 v80, 48, v225
	s_nop 0
	v_cndmask_b32_e32 v102, v202, v102, vcc
	v_cmp_gt_u32_e32 vcc, s35, v80
	v_add_u32_e32 v80, 16, v225
	s_nop 0
	v_cndmask_b32_e32 v119, v202, v119, vcc
	v_cmp_gt_u32_e32 vcc, s35, v80
	v_add_u32_e32 v80, 43, v225
	s_nop 0
	v_cndmask_b32_e32 v103, v202, v103, vcc
	v_cmp_gt_u32_e32 vcc, s35, v80
	v_add_u32_e32 v80, 11, v225
	s_nop 0
	v_cndmask_b32_e32 v120, v202, v120, vcc
	v_cmp_gt_u32_e32 vcc, s35, v80
	v_add_u32_e32 v80, 42, v225
	s_nop 0
	v_cndmask_b32_e32 v104, v202, v104, vcc
	v_cmp_gt_u32_e32 vcc, s35, v80
	v_add_u32_e32 v80, 10, v225
	s_nop 0
	v_cndmask_b32_e32 v121, v202, v121, vcc
	v_cmp_gt_u32_e32 vcc, s35, v80
	v_add_u32_e32 v80, 41, v225
	s_nop 0
	v_cndmask_b32_e32 v105, v202, v105, vcc
	v_cmp_gt_u32_e32 vcc, s35, v80
	v_add_u32_e32 v80, 9, v225
	s_nop 0
	v_cndmask_b32_e32 v122, v202, v122, vcc
	v_cmp_gt_u32_e32 vcc, s35, v80
	v_add_u32_e32 v80, 40, v225
	s_nop 0
	v_cndmask_b32_e32 v106, v202, v106, vcc
	v_cmp_gt_u32_e32 vcc, s35, v80
	v_add_u32_e32 v80, 8, v225
	s_nop 0
	v_cndmask_b32_e32 v123, v202, v123, vcc
	v_cmp_gt_u32_e32 vcc, s35, v80
	v_add_u32_e32 v80, 35, v225
	s_nop 0
	v_cndmask_b32_e32 v107, v202, v107, vcc
	v_cmp_gt_u32_e32 vcc, s35, v80
	v_add_u32_e32 v80, 3, v225
	s_nop 0
	v_cndmask_b32_e32 v124, v202, v124, vcc
	v_cmp_gt_u32_e32 vcc, s35, v80
	v_add_u32_e32 v80, 34, v225
	s_nop 0
	v_cndmask_b32_e32 v108, v202, v108, vcc
	v_cmp_gt_u32_e32 vcc, s35, v80
	v_add_u32_e32 v80, 2, v225
	s_nop 0
	v_cndmask_b32_e32 v125, v202, v125, vcc
	v_cmp_gt_u32_e32 vcc, s35, v80
	v_add_u32_e32 v80, 33, v225
	s_nop 0
	v_cndmask_b32_e32 v109, v202, v109, vcc
	v_cmp_gt_u32_e32 vcc, s35, v80
	v_add_u32_e32 v80, 1, v225
	s_nop 0
	v_cndmask_b32_e32 v126, v202, v126, vcc
	v_cmp_gt_u32_e32 vcc, s35, v80
	v_add_u32_e32 v80, 32, v225
	s_nop 0
	v_cndmask_b32_e32 v110, v202, v110, vcc
	v_cmp_gt_u32_e32 vcc, s35, v80
	s_nop 1
	v_cndmask_b32_e32 v127, v202, v127, vcc
	v_cmp_gt_u32_e32 vcc, s35, v225
	s_nop 1
	v_cndmask_b32_e32 v111, v202, v111, vcc

.LBB0_844:
	s_setprio 1
	ds_read_b128 v[114:117], v227 offset:49152
	ds_read_b128 v[118:121], v227 offset:57344
	ds_read_b128 v[122:125], v228 offset:49152
	ds_read_b128 v[232:235], v228 offset:57344
	s_add_i32 s14, s82, -1
	ds_read_b128 v[236:239], v229 offset:49152
	ds_read_b128 v[240:243], v229 offset:57344
	s_waitcnt lgkmcnt(5)
	v_mfma_f32_32x32x16_bf16 v[96:111], v[114:117], v[130:133], v[64:79]
	s_waitcnt lgkmcnt(4)
	v_mfma_f32_32x32x16_bf16 v[80:95], v[118:121], v[130:133], v[64:79]
	ds_read_b128 v[114:117], v230 offset:49152
	ds_read_b128 v[118:121], v230 offset:57344
	s_waitcnt lgkmcnt(5)
	v_mfma_f32_32x32x16_bf16 v[96:111], v[122:125], v[134:137], v[96:111]
	s_waitcnt lgkmcnt(4)
	v_mfma_f32_32x32x16_bf16 v[80:95], v[232:235], v[134:137], v[80:95]
	ds_read_b128 v[122:125], v227 offset:49280
	ds_read_b128 v[232:235], v227 offset:57472
	s_waitcnt lgkmcnt(5)
	v_mfma_f32_32x32x16_bf16 v[96:111], v[236:239], v[138:141], v[96:111]
	s_waitcnt lgkmcnt(4)
	v_mfma_f32_32x32x16_bf16 v[80:95], v[240:243], v[138:141], v[80:95]
	ds_read_b128 v[236:239], v228 offset:49280
	ds_read_b128 v[240:243], v228 offset:57472
	s_waitcnt lgkmcnt(5)
	v_mfma_f32_32x32x16_bf16 v[96:111], v[114:117], v[142:145], v[96:111]
	s_waitcnt lgkmcnt(4)
	v_mfma_f32_32x32x16_bf16 v[80:95], v[118:121], v[142:145], v[80:95]
	ds_read_b128 v[114:117], v229 offset:49280
	ds_read_b128 v[118:121], v229 offset:57472
	s_waitcnt lgkmcnt(5)
	v_mfma_f32_32x32x16_bf16 v[96:111], v[122:125], v[162:165], v[96:111]
	s_waitcnt lgkmcnt(4)
	v_mfma_f32_32x32x16_bf16 v[80:95], v[232:235], v[162:165], v[80:95]
	ds_read_b128 v[122:125], v230 offset:49280
	ds_read_b128 v[232:235], v230 offset:57472
	s_waitcnt lgkmcnt(5)
	v_mfma_f32_32x32x16_bf16 v[96:111], v[236:239], v[166:169], v[96:111]
	s_waitcnt lgkmcnt(4)
	v_mfma_f32_32x32x16_bf16 v[80:95], v[240:243], v[166:169], v[80:95]
	v_add_u32_e32 v126, v224, v220
	ds_read_b128 v[236:239], v126 offset:4096
	ds_read_b128 v[240:243], v126
	ds_read_b128 v[244:247], v213
	s_waitcnt lgkmcnt(6)
	v_mfma_f32_32x32x16_bf16 v[96:111], v[114:117], v[170:173], v[96:111]
	s_waitcnt lgkmcnt(5)
	v_mfma_f32_32x32x16_bf16 v[80:95], v[118:121], v[170:173], v[80:95]
	v_add_u32_e32 v118, v224, v221
	ds_read_b128 v[114:117], v118 offset:4096
	ds_read_b128 v[118:121], v118
	ds_read_b128 v[248:251], v213 offset:1024
	s_waitcnt lgkmcnt(7)
	v_mfma_f32_32x32x16_bf16 v[96:111], v[122:125], v[174:177], v[96:111]
	s_waitcnt lgkmcnt(6)
	v_mfma_f32_32x32x16_bf16 v[80:95], v[232:235], v[174:177], v[80:95]
	v_add_u32_e32 v126, v224, v222
	ds_read_b128 v[122:125], v126 offset:4096
	ds_read_b128 v[232:235], v126
	ds_read_b128 v[178:181], v213 offset:2048
	s_waitcnt lgkmcnt(6)
	v_mfma_f32_32x32x16_bf16 v[96:111], v[240:243], v[244:247], v[96:111]
	v_mfma_f32_32x32x16_bf16 v[80:95], v[236:239], v[244:247], v[80:95]
	v_add_u32_e32 v126, v224, v223
	ds_read_b128 v[236:239], v126 offset:4096
	ds_read_b128 v[240:243], v126
	ds_read_b128 v[244:247], v213 offset:3072
	s_waitcnt lgkmcnt(6)
	v_mfma_f32_32x32x16_bf16 v[96:111], v[118:121], v[248:251], v[96:111]
	v_mfma_f32_32x32x16_bf16 v[80:95], v[114:117], v[248:251], v[80:95]
	s_waitcnt lgkmcnt(3)
	v_mfma_f32_32x32x16_bf16 v[96:111], v[232:235], v[178:181], v[96:111]
	v_mfma_f32_32x32x16_bf16 v[80:95], v[122:125], v[178:181], v[80:95]
	s_waitcnt lgkmcnt(0)
	v_mfma_f32_32x32x16_bf16 v[96:111], v[240:243], v[244:247], v[96:111]
	v_mfma_f32_32x32x16_bf16 v[80:95], v[236:239], v[244:247], v[80:95]
	s_setprio 0
	s_cmp_le_i32 s14, s12
	s_cselect_b64 s[14:15], -1, 0
	s_cmp_gt_i32 s50, s22
	s_cselect_b64 s[44:45], -1, 0
	s_and_b64 s[14:15], s[14:15], s[44:45]
	s_and_b64 vcc, exec, s[14:15]
	s_cbranch_vccnz .LBB0_846
	v_add_u32_e32 v114, -5, v225
	v_cmp_gt_u32_e32 vcc, s35, v114
	v_subrev_u32_e32 v114, 37, v225
	s_nop 0
	v_cndmask_b32_e32 v96, v202, v96, vcc
	v_cmp_gt_u32_e32 vcc, s35, v114
	v_add_u32_e32 v114, -6, v225
	s_nop 0
	v_cndmask_b32_e32 v80, v202, v80, vcc
	v_cmp_gt_u32_e32 vcc, s35, v114
	v_subrev_u32_e32 v114, 38, v225
	s_nop 0
	v_cndmask_b32_e32 v97, v202, v97, vcc
	v_cmp_gt_u32_e32 vcc, s35, v114
	v_add_u32_e32 v114, -7, v225
	s_nop 0
	v_cndmask_b32_e32 v81, v202, v81, vcc
	v_cmp_gt_u32_e32 vcc, s35, v114
	v_subrev_u32_e32 v114, 39, v225
	s_nop 0
	v_cndmask_b32_e32 v98, v202, v98, vcc
	v_cmp_gt_u32_e32 vcc, s35, v114
	v_add_u32_e32 v114, -8, v225
	s_nop 0
	v_cndmask_b32_e32 v82, v202, v82, vcc
	v_cmp_gt_u32_e32 vcc, s35, v114
	v_subrev_u32_e32 v114, 40, v225
	s_nop 0
	v_cndmask_b32_e32 v99, v202, v99, vcc
	v_cmp_gt_u32_e32 vcc, s35, v114
	v_add_u32_e32 v114, -13, v225
	s_nop 0
	v_cndmask_b32_e32 v83, v202, v83, vcc
	v_cmp_gt_u32_e32 vcc, s35, v114
	v_subrev_u32_e32 v114, 45, v225
	s_nop 0
	v_cndmask_b32_e32 v100, v202, v100, vcc
	v_cmp_gt_u32_e32 vcc, s35, v114
	v_add_u32_e32 v114, -14, v225
	s_nop 0
	v_cndmask_b32_e32 v84, v202, v84, vcc
	v_cmp_gt_u32_e32 vcc, s35, v114
	v_subrev_u32_e32 v114, 46, v225
	s_nop 0
	v_cndmask_b32_e32 v101, v202, v101, vcc
	v_cmp_gt_u32_e32 vcc, s35, v114
	v_add_u32_e32 v114, -15, v225
	s_nop 0
	v_cndmask_b32_e32 v85, v202, v85, vcc
	v_cmp_gt_u32_e32 vcc, s35, v114
	v_subrev_u32_e32 v114, 47, v225
	s_nop 0
	v_cndmask_b32_e32 v102, v202, v102, vcc
	v_cmp_gt_u32_e32 vcc, s35, v114
	v_add_u32_e32 v114, -16, v225
	s_nop 0
	v_cndmask_b32_e32 v86, v202, v86, vcc
	v_cmp_gt_u32_e32 vcc, s35, v114
	v_subrev_u32_e32 v114, 48, v225
	s_nop 0
	v_cndmask_b32_e32 v103, v202, v103, vcc
	v_cmp_gt_u32_e32 vcc, s35, v114
	v_subrev_u32_e32 v114, 21, v225
	s_nop 0
	v_cndmask_b32_e32 v87, v202, v87, vcc
	v_cmp_gt_u32_e32 vcc, s35, v114
	v_subrev_u32_e32 v114, 53, v225
	s_nop 0
	v_cndmask_b32_e32 v104, v202, v104, vcc
	v_cmp_gt_u32_e32 vcc, s35, v114
	v_subrev_u32_e32 v114, 22, v225
	s_nop 0
	v_cndmask_b32_e32 v88, v202, v88, vcc
	v_cmp_gt_u32_e32 vcc, s35, v114
	v_subrev_u32_e32 v114, 54, v225
	s_nop 0
	v_cndmask_b32_e32 v105, v202, v105, vcc
	v_cmp_gt_u32_e32 vcc, s35, v114
	v_subrev_u32_e32 v114, 23, v225
	s_nop 0
	v_cndmask_b32_e32 v89, v202, v89, vcc
	v_cmp_gt_u32_e32 vcc, s35, v114
	v_subrev_u32_e32 v114, 55, v225
	s_nop 0
	v_cndmask_b32_e32 v106, v202, v106, vcc
	v_cmp_gt_u32_e32 vcc, s35, v114
	v_subrev_u32_e32 v114, 24, v225
	s_nop 0
	v_cndmask_b32_e32 v90, v202, v90, vcc
	v_cmp_gt_u32_e32 vcc, s35, v114
	v_subrev_u32_e32 v114, 56, v225
	s_nop 0
	v_cndmask_b32_e32 v107, v202, v107, vcc
	v_cmp_gt_u32_e32 vcc, s35, v114
	v_subrev_u32_e32 v114, 29, v225
	s_nop 0
	v_cndmask_b32_e32 v91, v202, v91, vcc
	v_cmp_gt_u32_e32 vcc, s35, v114
	v_subrev_u32_e32 v114, 61, v225
	s_nop 0
	v_cndmask_b32_e32 v108, v202, v108, vcc
	v_cmp_gt_u32_e32 vcc, s35, v114
	v_subrev_u32_e32 v114, 30, v225
	s_nop 0
	v_cndmask_b32_e32 v92, v202, v92, vcc
	v_cmp_gt_u32_e32 vcc, s35, v114
	v_subrev_u32_e32 v114, 62, v225
	s_nop 0
	v_cndmask_b32_e32 v109, v202, v109, vcc
	v_cmp_gt_u32_e32 vcc, s35, v114
	v_subrev_u32_e32 v114, 31, v225
	s_nop 0
	v_cndmask_b32_e32 v93, v202, v93, vcc
	v_cmp_gt_u32_e32 vcc, s35, v114
	v_subrev_u32_e32 v114, 63, v225
	s_nop 0
	v_cndmask_b32_e32 v110, v202, v110, vcc
	v_cmp_gt_u32_e32 vcc, s35, v114
	v_subrev_u32_e32 v114, 32, v225
	s_nop 0
	v_cndmask_b32_e32 v94, v202, v94, vcc
	v_cmp_gt_u32_e32 vcc, s35, v114
	v_subrev_u32_e32 v114, 64, v225
	s_nop 0
	v_cndmask_b32_e32 v111, v202, v111, vcc
	v_cmp_gt_u32_e32 vcc, s35, v114
	s_nop 1
	v_cndmask_b32_e32 v95, v202, v95, vcc
